# NSA selected/window tile loops: second-half K-fragment LDS reads interleaved with the first-half QK^T MFMAs (on saddr + equal priority + peeled iteration)
# speedup vs baseline: 1.0030x; 1.0030x over previous
; #define SBAR() __builtin_amdgcn_sched_barrier(0)
; DI int crow(int r, int hi) { return (r & 3) + 8 * (r >> 2) + 4 * hi; }
; #pragma unroll
;     for (int r = 0; r < 16; ++r) { p0[r] = 0.f; p1[r] = 0.f; }
;     int rowb = r32 * (2 * D), swz = (r32 & 7) << 4; asm volatile("" : "+v"(rowb), "+v"(swz));
; #pragma unroll
;     for (int g4 = 0; g4 < D / (16 * NBT); ++g4) {
;         bf16x8 kf[2 * NBT];
; #pragma unroll
;         for (int i = 0; i < NBT; ++i) { const int cb = ((g4 * NBT + i) * 16 + hi * 8) * 2;
;             const char* kp = Ks + rowb + (cb ^ swz);
;             kf[2 * i] = *reinterpret_cast<const bf16x8*>(kp);
;             kf[2 * i + 1] = *reinterpret_cast<const bf16x8*>(kp + 64 * D); }
;         SBAR();
; #pragma unroll
;         for (int i = 0; i < NBT; ++i) {
;             p0 = __builtin_amdgcn_mfma_f32_32x32x16_bf16(kf[2 * i], qr[g4 * NBT + i], p0, 0, 0, 0);
;             p1 = __builtin_amdgcn_mfma_f32_32x32x16_bf16(kf[2 * i + 1], qr[g4 * NBT + i], p1, 0, 0, 0); }
;         SBAR();
;     }
; }
; template <int D, class MaskF>
; DI void tile_finish(Core<D>& c, f32x16& p0, f32x16& p1, int j, const MaskF& mk, float* ws, int vb, int r32, int hi) {
;     if (mk.partial(j)) { const int kb = 64 * j;
; #pragma unroll
;         for (int r = 0; r < 16; ++r) { const int k0 = kb + crow(r, hi); if (!mk.ok(j, k0)) p0[r] = NEGS; if (!mk.ok(j, k0 + 32)) p1[r] = NEGS; } }
.LBB0_862:
	s_lshl_b32 s61, s10, 14
	v_mov_b32_e32 v0, v171
	v_mov_b32_e32 v177, v204
	s_add_i32 s14, s61, 0
	v_add_u32_e32 v74, 32, v205
	v_add_u32_e32 v0, s14, v0
	v_xad_u32 v70, v177, v205, v0
	v_xad_u32 v74, v177, v74, v0
	ds_read_b128 v[66:69], v70
	ds_read_b128 v[70:73], v70 offset:8192
	ds_read_b128 v[194:197], v74
	ds_read_b128 v[220:223], v74 offset:8192
	v_add_u32_e32 v74, 64, v205
	v_xad_u32 v74, v177, v74, v0
	ds_read_b128 v[224:227], v74
	ds_read_b128 v[228:231], v74 offset:8192
	v_add_u32_e32 v74, 0x60, v205
	v_xad_u32 v74, v177, v74, v0
	ds_read_b128 v[232:235], v74
	ds_read_b128 v[236:239], v74 offset:8192
	s_waitcnt lgkmcnt(7)
	v_mfma_f32_32x32x16_bf16 v[82:97], v[66:69], v[112:115], 0
	s_waitcnt lgkmcnt(6)
	v_mfma_f32_32x32x16_bf16 v[66:81], v[70:73], v[112:115], 0
	s_waitcnt lgkmcnt(5)
	v_mfma_f32_32x32x16_bf16 v[82:97], v[194:197], v[116:119], v[82:97]
	v_xad_u32 v186, v177, v209, v0
	ds_read_b128 v[194:197], v186
	s_waitcnt lgkmcnt(5)
	v_mfma_f32_32x32x16_bf16 v[66:81], v[220:223], v[116:119], v[66:81]
	ds_read_b128 v[220:223], v186 offset:8192
	v_xad_u32 v186, v177, v210, v0
	s_waitcnt lgkmcnt(5)
	v_mfma_f32_32x32x16_bf16 v[82:97], v[224:227], v[120:123], v[82:97]
	ds_read_b128 v[224:227], v186
	s_waitcnt lgkmcnt(5)
	v_mfma_f32_32x32x16_bf16 v[66:81], v[228:231], v[120:123], v[66:81]
	ds_read_b128 v[228:231], v186 offset:8192
	v_xad_u32 v186, v177, v211, v0
	v_xad_u32 v0, v177, v212, v0
	s_waitcnt lgkmcnt(5)
	v_mfma_f32_32x32x16_bf16 v[82:97], v[232:235], v[124:127], v[82:97]
	ds_read_b128 v[232:235], v186
	s_waitcnt lgkmcnt(5)
	v_mfma_f32_32x32x16_bf16 v[66:81], v[236:239], v[124:127], v[66:81]
	ds_read_b128 v[236:239], v186 offset:8192
	ds_read_b128 v[248:251], v0
	ds_read_b128 v[186:189], v0 offset:8192
	s_waitcnt lgkmcnt(7)
	v_mfma_f32_32x32x16_bf16 v[82:97], v[194:197], v[128:131], v[82:97]
	s_waitcnt lgkmcnt(6)
	v_mfma_f32_32x32x16_bf16 v[66:81], v[220:223], v[128:131], v[66:81]
	s_waitcnt lgkmcnt(5)
	v_mfma_f32_32x32x16_bf16 v[82:97], v[224:227], v[132:135], v[82:97]
	s_waitcnt lgkmcnt(4)
	v_mfma_f32_32x32x16_bf16 v[66:81], v[228:231], v[132:135], v[66:81]
	s_waitcnt lgkmcnt(3)
	v_mfma_f32_32x32x16_bf16 v[82:97], v[232:235], v[136:139], v[82:97]
	s_waitcnt lgkmcnt(2)
	v_mfma_f32_32x32x16_bf16 v[66:81], v[236:239], v[136:139], v[66:81]
	s_waitcnt lgkmcnt(1)
	v_mfma_f32_32x32x16_bf16 v[82:97], v[248:251], v[140:143], v[82:97]
	s_waitcnt lgkmcnt(0)
	v_mfma_f32_32x32x16_bf16 v[66:81], v[186:189], v[140:143], v[66:81]
	s_cmp_lt_i32 s59, s91
	s_cbranch_scc1 .LBB0_866
	v_lshl_add_u32 v0, s59, 6, v206
	v_add_u32_e32 v177, 32, v0
	v_cmp_le_i32_e64 s[14:15], v177, v169
	v_add_u32_e32 v177, 33, v0
	v_cmp_le_i32_e64 s[16:17], v177, v169
	v_or_b32_e32 v177, 2, v0
	v_cmp_le_i32_e32 vcc, v0, v169
	s_nop 2
	v_cndmask_b32_e64 v67, v247, v67, s[16:17]
	v_cmp_le_i32_e64 s[16:17], v177, v169
	v_add_u32_e32 v177, 34, v0
	v_cmp_le_i32_e64 s[18:19], v177, v169
	v_or_b32_e32 v177, 3, v0
	v_cndmask_b32_e64 v66, v247, v66, s[14:15]
	v_cndmask_b32_e64 v68, v247, v68, s[18:19]
	v_cmp_le_i32_e64 s[18:19], v177, v169
	v_add_u32_e32 v177, 35, v0
	v_cmp_le_i32_e64 s[20:21], v177, v169
	v_add_u32_e32 v177, 8, v0
	v_cmp_lt_i32_e64 s[14:15], v0, v169
	v_cndmask_b32_e64 v69, v247, v69, s[20:21]
	v_cmp_le_i32_e64 s[20:21], v177, v169
	v_add_u32_e32 v177, 40, v0
	v_cmp_le_i32_e64 s[22:23], v177, v169
	v_add_u32_e32 v177, 9, v0
	s_nop 0
	v_cndmask_b32_e64 v70, v247, v70, s[22:23]
	v_cmp_le_i32_e64 s[22:23], v177, v169
	v_add_u32_e32 v177, 41, v0
	v_cmp_le_i32_e64 s[24:25], v177, v169
	v_add_u32_e32 v177, 10, v0
	s_nop 0
	v_cndmask_b32_e64 v71, v247, v71, s[24:25]
	v_cmp_le_i32_e64 s[24:25], v177, v169
	v_add_u32_e32 v177, 42, v0
	v_cmp_le_i32_e64 s[26:27], v177, v169
	v_add_u32_e32 v177, 11, v0
	s_nop 0
	v_cndmask_b32_e64 v72, v247, v72, s[26:27]
	v_cmp_le_i32_e64 s[26:27], v177, v169
	v_add_u32_e32 v177, 43, v0
	v_cmp_le_i32_e64 s[28:29], v177, v169
	v_add_u32_e32 v177, 16, v0
	s_nop 0
	v_cndmask_b32_e64 v73, v247, v73, s[28:29]
	v_cmp_le_i32_e64 s[28:29], v177, v169
	v_add_u32_e32 v177, 48, v0
	v_cmp_le_i32_e64 s[30:31], v177, v169
	v_add_u32_e32 v177, 17, v0
	s_nop 0
	v_cndmask_b32_e64 v74, v247, v74, s[30:31]
	v_cmp_le_i32_e64 s[30:31], v177, v169
	v_add_u32_e32 v177, 49, v0
	v_cmp_le_i32_e64 s[34:35], v177, v169
	v_add_u32_e32 v177, 18, v0
	s_nop 0
	v_cndmask_b32_e64 v75, v247, v75, s[34:35]
	v_cmp_le_i32_e64 s[34:35], v177, v169
	v_add_u32_e32 v177, 50, v0
	v_cmp_le_i32_e64 s[36:37], v177, v169
	v_add_u32_e32 v177, 19, v0
	s_nop 0
	v_cndmask_b32_e64 v76, v247, v76, s[36:37]
	v_cmp_le_i32_e64 s[36:37], v177, v169
	v_add_u32_e32 v177, 51, v0
	v_cmp_le_i32_e64 s[38:39], v177, v169
	v_add_u32_e32 v177, 24, v0
	s_nop 0
	v_cndmask_b32_e64 v77, v247, v77, s[38:39]
	v_cmp_le_i32_e64 s[38:39], v177, v169
	v_add_u32_e32 v177, 56, v0
	v_cmp_le_i32_e64 s[40:41], v177, v169
	v_add_u32_e32 v177, 25, v0
	s_nop 0
	v_cndmask_b32_e64 v78, v247, v78, s[40:41]
	v_cmp_le_i32_e64 s[40:41], v177, v169
	v_add_u32_e32 v177, 57, v0
	v_cmp_le_i32_e64 s[42:43], v177, v169
	v_add_u32_e32 v177, 26, v0
	s_nop 0
	v_cndmask_b32_e64 v79, v247, v79, s[42:43]
	v_cmp_le_i32_e64 s[42:43], v177, v169
	v_add_u32_e32 v177, 58, v0
	v_cmp_le_i32_e64 s[44:45], v177, v169
	v_add_u32_e32 v177, 27, v0
	v_add_u32_e32 v0, 59, v0
	v_cndmask_b32_e64 v80, v247, v80, s[44:45]
	v_cmp_le_i32_e64 s[44:45], v177, v169
	v_cmp_gt_i32_e64 s[46:47], v0, v169
	s_and_saveexec_b64 s[54:55], s[46:47]
	v_mov_b32_e32 v81, s95
	s_or_b64 exec, exec, s[54:55]
	v_cndmask_b32_e64 v83, v247, v83, s[14:15]
	v_cndmask_b32_e32 v82, v247, v82, vcc
	v_cndmask_b32_e64 v84, v247, v84, s[16:17]
	v_cndmask_b32_e64 v85, v247, v85, s[18:19]
	v_cndmask_b32_e64 v86, v247, v86, s[20:21]
	v_cndmask_b32_e64 v87, v247, v87, s[22:23]
	v_cndmask_b32_e64 v88, v247, v88, s[24:25]
	v_cndmask_b32_e64 v89, v247, v89, s[26:27]
	v_cndmask_b32_e64 v90, v247, v90, s[28:29]
	v_cndmask_b32_e64 v91, v247, v91, s[30:31]
	v_cndmask_b32_e64 v92, v247, v92, s[34:35]
	v_cndmask_b32_e64 v93, v247, v93, s[36:37]
	v_cndmask_b32_e64 v94, v247, v94, s[38:39]
	v_cndmask_b32_e64 v95, v247, v95, s[40:41]
	v_cndmask_b32_e64 v96, v247, v96, s[42:43]
	v_cndmask_b32_e64 v97, v247, v97, s[44:45]

; #define SBAR() __builtin_amdgcn_sched_barrier(0)
; #pragma unroll
;     for (int r = 0; r < 16; ++r) { p0[r] = 0.f; p1[r] = 0.f; }
;     int rowb = r32 * (2 * D), swz = (r32 & 7) << 4; asm volatile("" : "+v"(rowb), "+v"(swz));
; #pragma unroll
;     for (int g4 = 0; g4 < D / (16 * NBT); ++g4) {
;         bf16x8 kf[2 * NBT];
; #pragma unroll
;         for (int i = 0; i < NBT; ++i) { const int cb = ((g4 * NBT + i) * 16 + hi * 8) * 2;
;             const char* kp = Ks + rowb + (cb ^ swz);
;             kf[2 * i] = *reinterpret_cast<const bf16x8*>(kp);
;             kf[2 * i + 1] = *reinterpret_cast<const bf16x8*>(kp + 64 * D); }
;         SBAR();
; #pragma unroll
;         for (int i = 0; i < NBT; ++i) {
;             p0 = __builtin_amdgcn_mfma_f32_32x32x16_bf16(kf[2 * i], qr[g4 * NBT + i], p0, 0, 0, 0);
;             p1 = __builtin_amdgcn_mfma_f32_32x32x16_bf16(kf[2 * i + 1], qr[g4 * NBT + i], p1, 0, 0, 0); }
;         SBAR();
;     }
; }
; template <int D, class MaskF>
; DI void tile_finish(Core<D>& c, f32x16& p0, f32x16& p1, int j, const MaskF& mk, float* ws, int vb, int r32, int hi) {
;     if (mk.partial(j)) { const int kb = 64 * j;
.LBB0_883:
	s_lshl_b32 s93, s10, 14
	s_add_i32 s14, s93, 0
	v_mov_b32_e32 v66, v175
	v_mov_b32_e32 v217, v176
	v_add_u32_e32 v74, 32, v177
	v_add_u32_e32 v234, s14, v66
	v_xad_u32 v70, v217, v177, v234
	v_xad_u32 v74, v217, v74, v234
	ds_read_b128 v[66:69], v70
	ds_read_b128 v[70:73], v70 offset:8192
	ds_read_b128 v[186:189], v74
	ds_read_b128 v[194:197], v74 offset:8192
	v_add_u32_e32 v74, 64, v177
	v_xad_u32 v74, v217, v74, v234
	ds_read_b128 v[218:221], v74
	ds_read_b128 v[222:225], v74 offset:8192
	v_xad_u32 v74, v217, v206, v234
	ds_read_b128 v[226:229], v74
	ds_read_b128 v[230:233], v74 offset:8192
	s_waitcnt lgkmcnt(7)
	v_mfma_f32_32x32x16_bf16 v[82:97], v[66:69], v[112:115], 0
	s_waitcnt lgkmcnt(6)
	v_mfma_f32_32x32x16_bf16 v[66:81], v[70:73], v[112:115], 0
	s_waitcnt lgkmcnt(5)
	v_mfma_f32_32x32x16_bf16 v[82:97], v[186:189], v[116:119], v[82:97]
	v_xad_u32 v238, v217, v207, v234
	v_xad_u32 v239, v217, v208, v234
	v_xad_u32 v253, v217, v209, v234
	v_xad_u32 v217, v217, v210, v234
	ds_read_b128 v[186:189], v238
	s_waitcnt lgkmcnt(5)
	v_mfma_f32_32x32x16_bf16 v[66:81], v[194:197], v[116:119], v[66:81]
	ds_read_b128 v[194:197], v238 offset:8192
	s_waitcnt lgkmcnt(5)
	v_mfma_f32_32x32x16_bf16 v[82:97], v[218:221], v[120:123], v[82:97]
	ds_read_b128 v[218:221], v239
	s_waitcnt lgkmcnt(5)
	v_mfma_f32_32x32x16_bf16 v[66:81], v[222:225], v[120:123], v[66:81]
	ds_read_b128 v[222:225], v239 offset:8192
	s_waitcnt lgkmcnt(5)
	v_mfma_f32_32x32x16_bf16 v[82:97], v[226:229], v[124:127], v[82:97]
	ds_read_b128 v[226:229], v253
	s_waitcnt lgkmcnt(5)
	v_mfma_f32_32x32x16_bf16 v[66:81], v[230:233], v[124:127], v[66:81]
	ds_read_b128 v[230:233], v253 offset:8192
	ds_read_b128 v[234:237], v217
	ds_read_b128 v[248:251], v217 offset:8192
	s_waitcnt lgkmcnt(7)
	v_mfma_f32_32x32x16_bf16 v[82:97], v[186:189], v[128:131], v[82:97]
	s_waitcnt lgkmcnt(6)
	v_mfma_f32_32x32x16_bf16 v[66:81], v[194:197], v[128:131], v[66:81]
	s_waitcnt lgkmcnt(5)
	v_mfma_f32_32x32x16_bf16 v[82:97], v[218:221], v[132:135], v[82:97]
	s_waitcnt lgkmcnt(4)
	v_mfma_f32_32x32x16_bf16 v[66:81], v[222:225], v[132:135], v[66:81]
	s_waitcnt lgkmcnt(3)
	v_mfma_f32_32x32x16_bf16 v[82:97], v[226:229], v[136:139], v[82:97]
	s_waitcnt lgkmcnt(2)
	v_mfma_f32_32x32x16_bf16 v[66:81], v[230:233], v[136:139], v[66:81]
	s_waitcnt lgkmcnt(1)
	v_mfma_f32_32x32x16_bf16 v[82:97], v[234:237], v[140:143], v[82:97]
	s_waitcnt lgkmcnt(0)
	v_mfma_f32_32x32x16_bf16 v[66:81], v[248:251], v[140:143], v[66:81]
	s_lshl_b32 s14, s92, 6
	s_or_b32 s15, s14, 63
	s_cmp_gt_i32 s15, s86
	s_cselect_b64 s[16:17], -1, 0
	s_cmp_le_i32 s14, s90
	s_cselect_b64 s[18:19], -1, 0
	s_or_b64 s[16:17], s[16:17], s[18:19]
	s_andn2_b64 vcc, exec, s[16:17]
	s_cbranch_vccnz .LBB0_887
; DI int crow(int r, int hi) { return (r & 3) + 8 * (r >> 2) + 4 * hi; }
; template <int D, class MaskF>
; DI void tile_finish(Core<D>& c, f32x16& p0, f32x16& p1, int j, const MaskF& mk, float* ws, int vb, int r32, int hi) {
;     if (mk.partial(j)) { const int kb = 64 * j;
; #pragma unroll
;         for (int r = 0; r < 16; ++r) { const int k0 = kb + crow(r, hi); if (!mk.ok(j, k0)) p0[r] = NEGS; if (!mk.ok(j, k0 + 32)) p1[r] = NEGS; } }
	v_add_u32_e32 v186, s14, v203
	v_add_u32_e32 v187, 32, v186
	v_cmp_le_i32_e64 s[16:17], v187, v169
	v_cmp_gt_i32_e64 s[18:19], v187, v174
	v_add_u32_e32 v187, 33, v186
	v_cmp_le_i32_e64 s[20:21], v187, v169
	v_cmp_gt_i32_e64 s[22:23], v187, v174
	s_and_b64 s[20:21], s[20:21], s[22:23]
	v_or_b32_e32 v187, 2, v186
	v_cndmask_b32_e64 v67, v247, v67, s[20:21]
	v_cmp_le_i32_e64 s[20:21], v187, v169
	v_cmp_gt_i32_e64 s[22:23], v187, v174
	v_add_u32_e32 v187, 34, v186
	v_cmp_le_i32_e64 s[24:25], v187, v169
	v_cmp_gt_i32_e64 s[26:27], v187, v174
	s_and_b64 s[24:25], s[24:25], s[26:27]
	v_or_b32_e32 v187, 3, v186
	v_cndmask_b32_e64 v68, v247, v68, s[24:25]
	v_cmp_le_i32_e64 s[24:25], v187, v169
	v_cmp_gt_i32_e64 s[26:27], v187, v174
	v_add_u32_e32 v187, 35, v186
	v_cmp_le_i32_e64 s[28:29], v187, v169
	v_cmp_gt_i32_e64 s[30:31], v187, v174
	s_and_b64 s[28:29], s[28:29], s[30:31]
	v_add_u32_e32 v187, 8, v186
	v_cndmask_b32_e64 v69, v247, v69, s[28:29]
	v_cmp_le_i32_e64 s[28:29], v187, v169
	v_cmp_gt_i32_e64 s[30:31], v187, v174
	v_add_u32_e32 v187, 40, v186
	v_cmp_le_i32_e64 s[34:35], v187, v169
	v_cmp_gt_i32_e64 s[36:37], v187, v174
	s_and_b64 s[34:35], s[34:35], s[36:37]
	v_add_u32_e32 v187, 9, v186
	v_cndmask_b32_e64 v70, v247, v70, s[34:35]
	v_cmp_le_i32_e64 s[34:35], v187, v169
	v_cmp_gt_i32_e64 s[36:37], v187, v174
	v_add_u32_e32 v187, 41, v186
	v_cmp_le_i32_e64 s[38:39], v187, v169
	v_cmp_gt_i32_e64 s[40:41], v187, v174
	s_and_b64 s[38:39], s[38:39], s[40:41]
	v_add_u32_e32 v187, 10, v186
	v_cndmask_b32_e64 v71, v247, v71, s[38:39]
	v_cmp_le_i32_e64 s[38:39], v187, v169
	v_cmp_gt_i32_e64 s[40:41], v187, v174
	v_add_u32_e32 v187, 42, v186
	v_cmp_le_i32_e64 s[42:43], v187, v169
	v_cmp_gt_i32_e64 s[44:45], v187, v174
	s_and_b64 s[42:43], s[42:43], s[44:45]
	v_add_u32_e32 v187, 11, v186
	v_cndmask_b32_e64 v72, v247, v72, s[42:43]
	v_cmp_le_i32_e64 s[42:43], v187, v169
	v_cmp_gt_i32_e64 s[44:45], v187, v174
	v_add_u32_e32 v187, 43, v186
	v_cmp_le_i32_e64 s[46:47], v187, v169
	v_cmp_gt_i32_e64 s[48:49], v187, v174
	s_and_b64 s[46:47], s[46:47], s[48:49]
	v_add_u32_e32 v187, 16, v186
	v_cndmask_b32_e64 v73, v247, v73, s[46:47]
	v_cmp_le_i32_e64 s[46:47], v187, v169
	v_cmp_gt_i32_e64 s[48:49], v187, v174
	v_add_u32_e32 v187, 48, v186
	v_cmp_le_i32_e64 s[50:51], v187, v169
	v_cmp_gt_i32_e64 s[52:53], v187, v174
	s_and_b64 s[50:51], s[50:51], s[52:53]
	v_add_u32_e32 v187, 17, v186
	v_cndmask_b32_e64 v74, v247, v74, s[50:51]
	v_cmp_le_i32_e64 s[50:51], v187, v169
	v_cmp_gt_i32_e64 s[52:53], v187, v174
	v_add_u32_e32 v187, 49, v186
	v_cmp_le_i32_e64 s[54:55], v187, v169
	v_cmp_gt_i32_e64 s[56:57], v187, v174
	s_and_b64 s[54:55], s[54:55], s[56:57]
	v_add_u32_e32 v187, 18, v186
	v_cndmask_b32_e64 v75, v247, v75, s[54:55]
	v_cmp_le_i32_e64 s[54:55], v187, v169
	v_cmp_gt_i32_e64 s[56:57], v187, v174
	v_add_u32_e32 v187, 50, v186
	v_cmp_le_i32_e64 s[58:59], v187, v169
	v_cmp_gt_i32_e64 s[60:61], v187, v174
	s_and_b64 s[58:59], s[58:59], s[60:61]
	v_add_u32_e32 v187, 19, v186
	v_cndmask_b32_e64 v76, v247, v76, s[58:59]
	v_cmp_le_i32_e64 s[58:59], v187, v169
	v_cmp_gt_i32_e64 s[60:61], v187, v174
	v_add_u32_e32 v187, 51, v186
	v_cmp_le_i32_e64 s[62:63], v187, v169
	v_cmp_gt_i32_e64 s[64:65], v187, v174
	s_and_b64 s[62:63], s[62:63], s[64:65]
	v_add_u32_e32 v187, 24, v186
	v_cndmask_b32_e64 v77, v247, v77, s[62:63]
	v_cmp_le_i32_e64 s[62:63], v187, v169
	v_cmp_gt_i32_e64 s[64:65], v187, v174
	v_add_u32_e32 v187, 56, v186
	v_cmp_le_i32_e64 s[66:67], v187, v169
	v_cmp_gt_i32_e64 s[68:69], v187, v174
	s_and_b64 s[66:67], s[66:67], s[68:69]
	v_add_u32_e32 v187, 25, v186
	v_cndmask_b32_e64 v78, v247, v78, s[66:67]
	v_cmp_le_i32_e64 s[66:67], v187, v169
	v_cmp_gt_i32_e64 s[68:69], v187, v174
	v_add_u32_e32 v187, 57, v186
	v_cmp_le_i32_e64 s[70:71], v187, v169
	v_cmp_gt_i32_e64 s[72:73], v187, v174
	s_and_b64 s[70:71], s[70:71], s[72:73]
	v_add_u32_e32 v187, 26, v186
	s_and_b64 s[16:17], s[16:17], s[18:19]
	v_cndmask_b32_e64 v79, v247, v79, s[70:71]
	v_cmp_le_i32_e64 s[70:71], v187, v169
	v_cmp_gt_i32_e64 s[72:73], v187, v174
	v_add_u32_e32 v187, 58, v186
	v_cmp_le_i32_e32 vcc, v186, v169
	v_cmp_gt_i32_e64 s[14:15], v186, v174
	v_cndmask_b32_e64 v66, v247, v66, s[16:17]
	v_cmp_lt_i32_e64 s[16:17], v186, v169
	v_cmp_ge_i32_e64 s[18:19], v186, v174
	v_cmp_le_i32_e64 s[74:75], v187, v169
	v_cmp_gt_i32_e64 s[76:77], v187, v174
	v_add_u32_e32 v187, 27, v186
	v_add_u32_e32 v186, 59, v186
	s_and_b64 s[74:75], s[74:75], s[76:77]
	v_cmp_gt_i32_e64 s[78:79], v186, v169
	v_cmp_le_i32_e64 s[80:81], v186, v174
	v_cndmask_b32_e64 v80, v247, v80, s[74:75]
	v_cmp_le_i32_e64 s[74:75], v187, v169
	v_cmp_gt_i32_e64 s[76:77], v187, v174
	s_or_b64 s[80:81], s[78:79], s[80:81]
	s_and_saveexec_b64 s[78:79], s[80:81]
	v_mov_b32_e32 v81, s95
	s_or_b64 exec, exec, s[78:79]
	s_and_b64 vcc, vcc, s[14:15]
	v_cndmask_b32_e32 v82, v247, v82, vcc
	s_and_b64 vcc, s[16:17], s[18:19]
	v_cndmask_b32_e32 v83, v247, v83, vcc
	s_and_b64 vcc, s[20:21], s[22:23]
	v_cndmask_b32_e32 v84, v247, v84, vcc
	s_and_b64 vcc, s[24:25], s[26:27]
	v_cndmask_b32_e32 v85, v247, v85, vcc
	s_and_b64 vcc, s[28:29], s[30:31]
	v_cndmask_b32_e32 v86, v247, v86, vcc
	s_and_b64 vcc, s[34:35], s[36:37]
	v_cndmask_b32_e32 v87, v247, v87, vcc
	s_and_b64 vcc, s[38:39], s[40:41]
	v_cndmask_b32_e32 v88, v247, v88, vcc
	s_and_b64 vcc, s[42:43], s[44:45]
	v_cndmask_b32_e32 v89, v247, v89, vcc
	s_and_b64 vcc, s[46:47], s[48:49]
	v_cndmask_b32_e32 v90, v247, v90, vcc
	s_and_b64 vcc, s[50:51], s[52:53]
	v_cndmask_b32_e32 v91, v247, v91, vcc
	s_and_b64 vcc, s[54:55], s[56:57]
	v_cndmask_b32_e32 v92, v247, v92, vcc
	s_and_b64 vcc, s[58:59], s[60:61]
	v_cndmask_b32_e32 v93, v247, v93, vcc
	s_and_b64 vcc, s[62:63], s[64:65]
	v_cndmask_b32_e32 v94, v247, v94, vcc
	s_and_b64 vcc, s[66:67], s[68:69]
	v_cndmask_b32_e32 v95, v247, v95, vcc
	s_and_b64 vcc, s[70:71], s[72:73]
	v_cndmask_b32_e32 v96, v247, v96, vcc
	s_and_b64 vcc, s[74:75], s[76:77]
	v_cndmask_b32_e32 v97, v247, v97, vcc
